# barrier poll loops: s_sleep 3 instead of s_sleep 1 (less polling pressure while stragglers finish)
# baseline (speedup 1.0000x reference)
; __device__ __forceinline__ unsigned xb_ld(unsigned* p)              { return __hip_atomic_load(p, __ATOMIC_RELAXED, __HIP_MEMORY_SCOPE_AGENT); }
; __device__ __forceinline__ void xcd_barrier_complete(unsigned* bar, unsigned x, unsigned& nloc, unsigned& nx) {
;     const unsigned G = gridDim.x * gridDim.y * gridDim.z;
;     unsigned sum, cnt, mine, sp = 0u;
;     for (;;) {
;         sum = 0u; cnt = 0u; mine = 0u;
; #pragma unroll
;         for (unsigned j = 0; j < 16; ++j) { const unsigned c = xb_ld(&bar[XB_XCNT(j)]); sum += c; cnt += (c > 0u) ? 1u : 0u; mine = (j == x) ? c : mine; }
;         if (sum == G) break;
;         __builtin_amdgcn_s_sleep(1);
;         if ((++sp & 255u) == 0u) { if (xb_ld(&bar[XB_TMO])) break; if (sp > XB_SPIN_CAP) { atomicAdd(&bar[XB_TMO], 1u); break; } }
;     }
.LBB0_104:
	global_load_dword v16, v17, s[8:9] sc1
	global_load_dword v1, v17, s[10:11] sc1
	global_load_dword v2, v17, s[14:15] sc1
	global_load_dword v3, v17, s[16:17] sc1
	global_load_dword v4, v17, s[18:19] sc1
	global_load_dword v5, v17, s[20:21] sc1
	global_load_dword v6, v17, s[22:23] sc1
	global_load_dword v7, v17, s[24:25] sc1
	global_load_dword v8, v17, s[26:27] sc1
	global_load_dword v9, v17, s[28:29] sc1
	global_load_dword v10, v17, s[30:31] sc1
	global_load_dword v11, v17, s[34:35] sc1
	global_load_dword v12, v17, s[36:37] sc1
	global_load_dword v13, v17, s[38:39] sc1
	global_load_dword v14, v17, s[40:41] sc1
	global_load_dword v15, v17, s[42:43] sc1
	s_mov_b64 s[44:45], -1
	s_mov_b64 s[46:47], -1
	s_waitcnt vmcnt(14)
	v_add_u32_e32 v18, v1, v16
	s_waitcnt vmcnt(13)
	v_add_u32_e32 v18, v18, v2
	s_waitcnt vmcnt(12)
	v_add_u32_e32 v18, v18, v3
	s_waitcnt vmcnt(11)
	v_add_u32_e32 v18, v18, v4
	s_waitcnt vmcnt(10)
	v_add_u32_e32 v18, v18, v5
	s_waitcnt vmcnt(9)
	v_add_u32_e32 v18, v18, v6
	s_waitcnt vmcnt(8)
	v_add_u32_e32 v18, v18, v7
	s_waitcnt vmcnt(7)
	v_add_u32_e32 v18, v18, v8
	s_waitcnt vmcnt(6)
	v_add_u32_e32 v18, v18, v9
	s_waitcnt vmcnt(5)
	v_add_u32_e32 v18, v18, v10
	s_waitcnt vmcnt(4)
	v_add_u32_e32 v18, v18, v11
	s_waitcnt vmcnt(3)
	v_add_u32_e32 v18, v18, v12
	s_waitcnt vmcnt(2)
	v_add_u32_e32 v18, v18, v13
	s_waitcnt vmcnt(1)
	v_add_u32_e32 v18, v18, v14
	s_waitcnt vmcnt(0)
	v_add_u32_e32 v18, v18, v15
	v_cmp_eq_u32_e32 vcc, s48, v18
	s_cbranch_vccnz .LBB0_103
	s_and_b32 s12, s49, 0xff
	s_cmp_eq_u32 s12, 0
	s_mov_b64 s[12:13], -1
	s_sleep 3
	s_cbranch_scc1 .LBB0_108
	s_and_b64 vcc, exec, s[12:13]
	s_cbranch_vccz .LBB0_103

.LBB0_121:
	s_and_b32 s13, s12, 0xff
	s_mov_b64 s[22:23], -1
	s_cmp_lg_u32 s13, 0
	s_mov_b64 s[26:27], -1
	s_sleep 3
	s_cbranch_scc0 .LBB0_124
	s_and_b64 vcc, exec, s[26:27]
	s_cbranch_vccz .LBB0_120

.LBB0_138:
	s_and_b32 s12, s26, 0xff
	s_cmp_lg_u32 s12, 0
	s_mov_b64 s[24:25], -1
	s_sleep 3
	s_cbranch_scc0 .LBB0_141
	s_mov_b64 s[12:13], -1
	s_and_b64 vcc, exec, s[24:25]
	s_cbranch_vccz .LBB0_137

; __device__ __forceinline__ unsigned xb_ld(unsigned* p)              { return __hip_atomic_load(p, __ATOMIC_RELAXED, __HIP_MEMORY_SCOPE_AGENT); }
; __device__ __forceinline__ void xcd_barrier_complete(unsigned* bar, unsigned x, unsigned& nloc, unsigned& nx) {
;     const unsigned G = gridDim.x * gridDim.y * gridDim.z;
;     unsigned sum, cnt, mine, sp = 0u;
;     for (;;) {
;         sum = 0u; cnt = 0u; mine = 0u;
; #pragma unroll
;         for (unsigned j = 0; j < 16; ++j) { const unsigned c = xb_ld(&bar[XB_XCNT(j)]); sum += c; cnt += (c > 0u) ? 1u : 0u; mine = (j == x) ? c : mine; }
;         if (sum == G) break;
;         __builtin_amdgcn_s_sleep(1);
;         if ((++sp & 255u) == 0u) { if (xb_ld(&bar[XB_TMO])) break; if (sp > XB_SPIN_CAP) { atomicAdd(&bar[XB_TMO], 1u); break; } }
;     }
.LBB0_177:
	global_load_dword v16, v17, s[6:7] sc1
	global_load_dword v1, v17, s[8:9] sc1
	global_load_dword v2, v17, s[10:11] sc1
	global_load_dword v3, v17, s[14:15] sc1
	global_load_dword v4, v17, s[16:17] sc1
	global_load_dword v5, v17, s[18:19] sc1
	global_load_dword v6, v17, s[20:21] sc1
	global_load_dword v7, v17, s[22:23] sc1
	global_load_dword v8, v17, s[24:25] sc1
	global_load_dword v9, v17, s[26:27] sc1
	global_load_dword v10, v17, s[28:29] sc1
	global_load_dword v11, v17, s[30:31] sc1
	global_load_dword v12, v17, s[34:35] sc1
	global_load_dword v13, v17, s[36:37] sc1
	global_load_dword v14, v17, s[38:39] sc1
	global_load_dword v15, v17, s[40:41] sc1
	s_mov_b64 s[42:43], -1
	s_mov_b64 s[44:45], -1
	s_waitcnt vmcnt(14)
	v_add_u32_e32 v18, v1, v16
	s_waitcnt vmcnt(13)
	v_add_u32_e32 v18, v18, v2
	s_waitcnt vmcnt(12)
	v_add_u32_e32 v18, v18, v3
	s_waitcnt vmcnt(11)
	v_add_u32_e32 v18, v18, v4
	s_waitcnt vmcnt(10)
	v_add_u32_e32 v18, v18, v5
	s_waitcnt vmcnt(9)
	v_add_u32_e32 v18, v18, v6
	s_waitcnt vmcnt(8)
	v_add_u32_e32 v18, v18, v7
	s_waitcnt vmcnt(7)
	v_add_u32_e32 v18, v18, v8
	s_waitcnt vmcnt(6)
	v_add_u32_e32 v18, v18, v9
	s_waitcnt vmcnt(5)
	v_add_u32_e32 v18, v18, v10
	s_waitcnt vmcnt(4)
	v_add_u32_e32 v18, v18, v11
	s_waitcnt vmcnt(3)
	v_add_u32_e32 v18, v18, v12
	s_waitcnt vmcnt(2)
	v_add_u32_e32 v18, v18, v13
	s_waitcnt vmcnt(1)
	v_add_u32_e32 v18, v18, v14
	s_waitcnt vmcnt(0)
	v_add_u32_e32 v18, v18, v15
	v_cmp_eq_u32_e32 vcc, s46, v18
	s_cbranch_vccnz .LBB0_176
	s_and_b32 s12, s47, 0xff
	s_cmp_eq_u32 s12, 0
	s_mov_b64 s[12:13], -1
	s_sleep 3
	s_cbranch_scc1 .LBB0_181
	s_and_b64 vcc, exec, s[12:13]
	s_cbranch_vccz .LBB0_176

.LBB0_193:
	s_and_b32 s13, s12, 0xff
	s_mov_b64 s[20:21], -1
	s_cmp_lg_u32 s13, 0
	s_mov_b64 s[24:25], -1
	s_sleep 3
	s_cbranch_scc0 .LBB0_196
	s_and_b64 vcc, exec, s[24:25]
	s_cbranch_vccz .LBB0_192

.LBB0_210:
	s_and_b32 s12, s24, 0xff
	s_cmp_lg_u32 s12, 0
	s_mov_b64 s[22:23], -1
	s_sleep 3
	s_cbranch_scc0 .LBB0_213
	s_mov_b64 s[12:13], -1
	s_and_b64 vcc, exec, s[22:23]
	s_cbranch_vccz .LBB0_209

; __device__ __forceinline__ unsigned xb_ld(unsigned* p)              { return __hip_atomic_load(p, __ATOMIC_RELAXED, __HIP_MEMORY_SCOPE_AGENT); }
; __device__ __forceinline__ void xcd_barrier_complete(unsigned* bar, unsigned x, unsigned& nloc, unsigned& nx) {
;     const unsigned G = gridDim.x * gridDim.y * gridDim.z;
;     unsigned sum, cnt, mine, sp = 0u;
;     for (;;) {
;         sum = 0u; cnt = 0u; mine = 0u;
; #pragma unroll
;         for (unsigned j = 0; j < 16; ++j) { const unsigned c = xb_ld(&bar[XB_XCNT(j)]); sum += c; cnt += (c > 0u) ? 1u : 0u; mine = (j == x) ? c : mine; }
;         if (sum == G) break;
;         __builtin_amdgcn_s_sleep(1);
;         if ((++sp & 255u) == 0u) { if (xb_ld(&bar[XB_TMO])) break; if (sp > XB_SPIN_CAP) { atomicAdd(&bar[XB_TMO], 1u); break; } }
;     }
.LBB0_285:
	v_readlane_b32 s4, v252, 57
	v_readlane_b32 s5, v252, 58
	s_mov_b64 s[6:7], -1
	s_nop 3
	global_load_dword v2, v3, s[4:5] sc1
	v_readlane_b32 s4, v252, 59
	v_readlane_b32 s5, v252, 60
	s_nop 4
	global_load_dword v4, v3, s[4:5] sc1
	v_readlane_b32 s4, v252, 61
	v_readlane_b32 s5, v252, 62
	s_waitcnt vmcnt(0)
	v_add_u32_e32 v19, v4, v2
	s_nop 2
	global_load_dword v5, v3, s[4:5] sc1
	v_readlane_b32 s4, v252, 63
	v_readlane_b32 s5, v253, 0
	s_waitcnt vmcnt(0)
	v_add_u32_e32 v19, v19, v5
	s_nop 2
	global_load_dword v6, v3, s[4:5] sc1
	v_readlane_b32 s4, v253, 1
	v_readlane_b32 s5, v253, 2
	s_waitcnt vmcnt(0)
	v_add_u32_e32 v19, v19, v6
	s_nop 2
	global_load_dword v7, v3, s[4:5] sc1
	v_readlane_b32 s4, v253, 3
	v_readlane_b32 s5, v253, 4
	s_waitcnt vmcnt(0)
	v_add_u32_e32 v19, v19, v7
	s_nop 2
	global_load_dword v8, v3, s[4:5] sc1
	v_readlane_b32 s4, v253, 5
	v_readlane_b32 s5, v253, 6
	s_waitcnt vmcnt(0)
	v_add_u32_e32 v19, v19, v8
	s_nop 2
	global_load_dword v9, v3, s[4:5] sc1
	v_readlane_b32 s4, v253, 7
	v_readlane_b32 s5, v253, 8
	s_waitcnt vmcnt(0)
	v_add_u32_e32 v19, v19, v9
	s_nop 2
	global_load_dword v10, v3, s[4:5] sc1
	v_readlane_b32 s4, v253, 9
	v_readlane_b32 s5, v253, 10
	s_waitcnt vmcnt(0)
	v_add_u32_e32 v19, v19, v10
	s_nop 2
	global_load_dword v11, v3, s[4:5] sc1
	v_readlane_b32 s4, v253, 11
	v_readlane_b32 s5, v253, 12
	s_waitcnt vmcnt(0)
	v_add_u32_e32 v19, v19, v11
	s_nop 2
	global_load_dword v12, v3, s[4:5] sc1
	v_readlane_b32 s4, v253, 13
	v_readlane_b32 s5, v253, 14
	s_waitcnt vmcnt(0)
	v_add_u32_e32 v19, v19, v12
	s_nop 2
	global_load_dword v13, v3, s[4:5] sc1
	v_readlane_b32 s4, v253, 15
	v_readlane_b32 s5, v253, 16
	s_waitcnt vmcnt(0)
	v_add_u32_e32 v19, v19, v13
	s_nop 2
	global_load_dword v14, v3, s[4:5] sc1
	v_readlane_b32 s4, v253, 17
	v_readlane_b32 s5, v253, 18
	s_waitcnt vmcnt(0)
	v_add_u32_e32 v19, v19, v14
	s_nop 2
	global_load_dword v15, v3, s[4:5] sc1
	v_readlane_b32 s4, v253, 19
	v_readlane_b32 s5, v253, 20
	s_waitcnt vmcnt(0)
	v_add_u32_e32 v19, v19, v15
	s_nop 2
	global_load_dword v16, v3, s[4:5] sc1
	v_readlane_b32 s4, v253, 21
	v_readlane_b32 s5, v253, 22
	s_waitcnt vmcnt(0)
	v_add_u32_e32 v19, v19, v16
	s_nop 2
	global_load_dword v17, v3, s[4:5] sc1
	v_readlane_b32 s4, v253, 23
	v_readlane_b32 s5, v253, 24
	s_waitcnt vmcnt(0)
	v_add_u32_e32 v19, v19, v17
	s_nop 2
	global_load_dword v18, v3, s[4:5] sc1
	s_mov_b64 s[4:5], -1
	s_waitcnt vmcnt(0)
	v_add_u32_e32 v19, v19, v18
	v_cmp_eq_u32_e32 vcc, s12, v19
	s_cbranch_vccnz .LBB0_284
	s_and_b32 s4, s13, 0xff
	s_cmp_eq_u32 s4, 0
	s_mov_b64 s[4:5], -1
	s_mov_b64 s[8:9], -1
	s_sleep 3
	s_cbranch_scc1 .LBB0_289
	s_and_b64 vcc, exec, s[8:9]
	s_cbranch_vccz .LBB0_284

.LBB0_301:
	s_and_b32 s13, s12, 0xff
	s_mov_b64 s[40:41], -1
	s_cmp_lg_u32 s13, 0
	s_mov_b64 s[44:45], -1
	s_sleep 3
	s_cbranch_scc0 .LBB0_304
	s_and_b64 vcc, exec, s[44:45]
	s_cbranch_vccz .LBB0_300

; __device__ __forceinline__ unsigned xb_ld(unsigned* p)              { return __hip_atomic_load(p, __ATOMIC_RELAXED, __HIP_MEMORY_SCOPE_AGENT); }
; __device__ __forceinline__ void xcd_barrier_complete(unsigned* bar, unsigned x, unsigned& nloc, unsigned& nx) {
;     const unsigned G = gridDim.x * gridDim.y * gridDim.z;
;     unsigned sum, cnt, mine, sp = 0u;
;     for (;;) {
;         sum = 0u; cnt = 0u; mine = 0u;
; #pragma unroll
;         for (unsigned j = 0; j < 16; ++j) { const unsigned c = xb_ld(&bar[XB_XCNT(j)]); sum += c; cnt += (c > 0u) ? 1u : 0u; mine = (j == x) ? c : mine; }
;         if (sum == G) break;
;         __builtin_amdgcn_s_sleep(1);
;         if ((++sp & 255u) == 0u) { if (xb_ld(&bar[XB_TMO])) break; if (sp > XB_SPIN_CAP) { atomicAdd(&bar[XB_TMO], 1u); break; } }
;     }
.LBB0_466:
	v_readlane_b32 s4, v252, 57
	v_readlane_b32 s5, v252, 58
	s_mov_b64 s[6:7], -1
	s_nop 3
	global_load_dword v2, v3, s[4:5] sc1
	v_readlane_b32 s4, v252, 59
	v_readlane_b32 s5, v252, 60
	s_nop 4
	global_load_dword v4, v3, s[4:5] sc1
	v_readlane_b32 s4, v252, 61
	v_readlane_b32 s5, v252, 62
	s_waitcnt vmcnt(0)
	v_add_u32_e32 v19, v4, v2
	s_nop 2
	global_load_dword v5, v3, s[4:5] sc1
	v_readlane_b32 s4, v252, 63
	v_readlane_b32 s5, v253, 0
	s_waitcnt vmcnt(0)
	v_add_u32_e32 v19, v19, v5
	s_nop 2
	global_load_dword v6, v3, s[4:5] sc1
	v_readlane_b32 s4, v253, 1
	v_readlane_b32 s5, v253, 2
	s_waitcnt vmcnt(0)
	v_add_u32_e32 v19, v19, v6
	s_nop 2
	global_load_dword v7, v3, s[4:5] sc1
	v_readlane_b32 s4, v253, 3
	v_readlane_b32 s5, v253, 4
	s_waitcnt vmcnt(0)
	v_add_u32_e32 v19, v19, v7
	s_nop 2
	global_load_dword v8, v3, s[4:5] sc1
	v_readlane_b32 s4, v253, 5
	v_readlane_b32 s5, v253, 6
	s_waitcnt vmcnt(0)
	v_add_u32_e32 v19, v19, v8
	s_nop 2
	global_load_dword v9, v3, s[4:5] sc1
	v_readlane_b32 s4, v253, 7
	v_readlane_b32 s5, v253, 8
	s_waitcnt vmcnt(0)
	v_add_u32_e32 v19, v19, v9
	s_nop 2
	global_load_dword v10, v3, s[4:5] sc1
	v_readlane_b32 s4, v253, 9
	v_readlane_b32 s5, v253, 10
	s_waitcnt vmcnt(0)
	v_add_u32_e32 v19, v19, v10
	s_nop 2
	global_load_dword v11, v3, s[4:5] sc1
	v_readlane_b32 s4, v253, 11
	v_readlane_b32 s5, v253, 12
	s_waitcnt vmcnt(0)
	v_add_u32_e32 v19, v19, v11
	s_nop 2
	global_load_dword v12, v3, s[4:5] sc1
	v_readlane_b32 s4, v253, 13
	v_readlane_b32 s5, v253, 14
	s_waitcnt vmcnt(0)
	v_add_u32_e32 v19, v19, v12
	s_nop 2
	global_load_dword v13, v3, s[4:5] sc1
	v_readlane_b32 s4, v253, 15
	v_readlane_b32 s5, v253, 16
	s_waitcnt vmcnt(0)
	v_add_u32_e32 v19, v19, v13
	s_nop 2
	global_load_dword v14, v3, s[4:5] sc1
	v_readlane_b32 s4, v253, 17
	v_readlane_b32 s5, v253, 18
	s_waitcnt vmcnt(0)
	v_add_u32_e32 v19, v19, v14
	s_nop 2
	global_load_dword v15, v3, s[4:5] sc1
	v_readlane_b32 s4, v253, 19
	v_readlane_b32 s5, v253, 20
	s_waitcnt vmcnt(0)
	v_add_u32_e32 v19, v19, v15
	s_nop 2
	global_load_dword v16, v3, s[4:5] sc1
	v_readlane_b32 s4, v253, 21
	v_readlane_b32 s5, v253, 22
	s_waitcnt vmcnt(0)
	v_add_u32_e32 v19, v19, v16
	s_nop 2
	global_load_dword v17, v3, s[4:5] sc1
	v_readlane_b32 s4, v253, 23
	v_readlane_b32 s5, v253, 24
	s_waitcnt vmcnt(0)
	v_add_u32_e32 v19, v19, v17
	s_nop 2
	global_load_dword v18, v3, s[4:5] sc1
	s_mov_b64 s[4:5], -1
	s_waitcnt vmcnt(0)
	v_add_u32_e32 v19, v19, v18
	v_cmp_eq_u32_e32 vcc, s10, v19
	s_cbranch_vccnz .LBB0_465
	s_and_b32 s4, s12, 0xff
	s_cmp_eq_u32 s4, 0
	s_mov_b64 s[4:5], -1
	s_mov_b64 s[8:9], -1
	s_sleep 3
	s_cbranch_scc1 .LBB0_470
	s_and_b64 vcc, exec, s[8:9]
	s_cbranch_vccz .LBB0_465

.LBB0_482:
	s_and_b32 s12, s10, 0xff
	s_mov_b64 s[40:41], -1
	s_cmp_lg_u32 s12, 0
	s_mov_b64 s[44:45], -1
	s_sleep 3
	s_cbranch_scc0 .LBB0_485
	s_and_b64 vcc, exec, s[44:45]
	s_cbranch_vccz .LBB0_481

.LBB0_664:
	s_and_b32 s13, s12, 0xff
	s_mov_b64 s[38:39], -1
	s_cmp_lg_u32 s13, 0
	s_mov_b64 s[42:43], -1
	s_sleep 3
	s_cbranch_scc0 .LBB0_667
	s_and_b64 vcc, exec, s[42:43]
	s_cbranch_vccz .LBB0_663

.LBB0_1030:
	s_and_b32 s12, s10, 0xff
	s_mov_b64 s[38:39], -1
	s_cmp_lg_u32 s12, 0
	s_mov_b64 s[42:43], -1
	s_sleep 3
	s_cbranch_scc0 .LBB0_1033
	s_and_b64 vcc, exec, s[42:43]
	s_cbranch_vccz .LBB0_1029

.LBB0_1114:
	s_and_b32 s13, s12, 0xff
	s_mov_b64 s[36:37], -1
	s_cmp_lg_u32 s13, 0
	s_mov_b64 s[40:41], -1
	s_sleep 3
	s_cbranch_scc0 .LBB0_1117
	s_and_b64 vcc, exec, s[40:41]
	s_cbranch_vccz .LBB0_1113

.LBB0_1407:
	s_and_b32 s12, s10, 0xff
	s_mov_b64 s[34:35], -1
	s_cmp_lg_u32 s12, 0
	s_mov_b64 s[38:39], -1
	s_sleep 3
	s_cbranch_scc0 .LBB0_1410
	s_and_b64 vcc, exec, s[38:39]
	s_cbranch_vccz .LBB0_1406
